# grid barrier: non-leader workgroups poll the cross-XCD release word (TOPGEN) directly instead of the per-XCD forward (XGEN)
# speedup vs baseline: 1.0302x; 1.0003x over previous
.LBB0_66:
	s_or_b64 exec, exec, s[8:9]
	v_cvt_f32_u32_e32 v4, v2
	s_waitcnt vmcnt(0)
	v_readfirstlane_b32 s6, v3
	v_sub_u32_e32 v3, 0, v2
	v_rcp_iflag_f32_e32 v4, v4
	v_add_u32_e32 v5, s6, v1
	v_mul_f32_e32 v4, 0x4f7ffffe, v4
	v_cvt_u32_f32_e32 v4, v4
	v_mul_lo_u32 v1, v3, v4
	v_mul_hi_u32 v1, v4, v1
	v_add_u32_e32 v1, v4, v1
	v_mul_hi_u32 v1, v5, v1
	v_mul_lo_u32 v3, v1, v2
	v_sub_u32_e32 v3, v5, v3
	v_add_u32_e32 v4, 1, v1
	v_cmp_ge_u32_e32 vcc, v3, v2
	s_nop 1
	v_cndmask_b32_e32 v1, v1, v4, vcc
	v_sub_u32_e32 v4, v3, v2
	v_cndmask_b32_e32 v3, v3, v4, vcc
	v_add_u32_e32 v4, 1, v1
	v_cmp_ge_u32_e32 vcc, v3, v2
	v_add_u32_e32 v3, 1, v5
	s_nop 0
	v_cndmask_b32_e32 v1, v1, v4, vcc
	v_mul_lo_u32 v4, v2, v1
	v_add_u32_e32 v2, v4, v2
	v_cmp_ne_u32_e32 vcc, v3, v2
	s_and_saveexec_b64 s[6:7], vcc
	s_xor_b64 s[6:7], exec, s[6:7]
	s_cbranch_execz .LBB0_80
	s_waitcnt lgkmcnt(0)
	v_mov_b32_e32 v0, 0x2000
	s_add_u32 s12, s96, 0x3500
	s_addc_u32 s13, s97, 0
	v_mov_b32_e32 v0, 0
	global_load_dword v0, v0, s[12:13] sc1
	s_waitcnt vmcnt(0)
	v_cmp_eq_u32_e32 vcc, v0, v1
	s_and_saveexec_b64 s[8:9], vcc
	s_cbranch_execz .LBB0_79
	s_add_u32 s10, s40, 0x4200
	s_addc_u32 s11, s41, 0
	s_mov_b32 s24, 1
	s_mov_b64 s[14:15], 0
	v_mov_b32_e32 v0, 0
	s_branch .LBB0_70

.LBB0_181:
	s_or_b64 exec, exec, s[8:9]
	v_cvt_f32_u32_e32 v5, v3
	s_waitcnt vmcnt(0)
	v_readfirstlane_b32 s0, v4
	v_sub_u32_e32 v4, 0, v3
	v_rcp_iflag_f32_e32 v5, v5
	v_add_u32_e32 v6, s0, v0
	v_mul_f32_e32 v5, 0x4f7ffffe, v5
	v_cvt_u32_f32_e32 v5, v5
	v_mul_lo_u32 v0, v4, v5
	v_mul_hi_u32 v0, v5, v0
	v_add_u32_e32 v0, v5, v0
	v_mul_hi_u32 v0, v6, v0
	v_mul_lo_u32 v4, v0, v3
	v_sub_u32_e32 v4, v6, v4
	v_add_u32_e32 v5, 1, v0
	v_cmp_ge_u32_e32 vcc, v4, v3
	s_nop 1
	v_cndmask_b32_e32 v0, v0, v5, vcc
	v_sub_u32_e32 v5, v4, v3
	v_cndmask_b32_e32 v4, v4, v5, vcc
	v_add_u32_e32 v5, 1, v0
	v_cmp_ge_u32_e32 vcc, v4, v3
	v_add_u32_e32 v4, 1, v6
	s_nop 0
	v_cndmask_b32_e32 v0, v0, v5, vcc
	v_mul_lo_u32 v5, v3, v0
	v_add_u32_e32 v3, v5, v3
	v_cmp_ne_u32_e32 vcc, v4, v3
	s_and_saveexec_b64 s[0:1], vcc
	s_xor_b64 s[8:9], exec, s[0:1]
	s_cbranch_execz .LBB0_195
	s_waitcnt lgkmcnt(0)
	s_add_u32 s0, s96, 0x3500
	s_addc_u32 s1, s97, 0
	global_load_dword v2, v1, s[0:1] sc1
	s_waitcnt vmcnt(0)
	v_cmp_eq_u32_e32 vcc, v2, v0
	s_and_saveexec_b64 s[10:11], vcc
	s_cbranch_execz .LBB0_194
	s_mov_b32 s19, 1
	s_mov_b64 s[12:13], 0
	s_branch .LBB0_185

.LBB0_859:
	s_or_b64 exec, exec, s[8:9]
	v_cvt_f32_u32_e32 v5, v3
	s_waitcnt vmcnt(0)
	v_readfirstlane_b32 s0, v4
	v_sub_u32_e32 v4, 0, v3
	v_rcp_iflag_f32_e32 v5, v5
	v_add_u32_e32 v6, s0, v0
	v_mul_f32_e32 v5, 0x4f7ffffe, v5
	v_cvt_u32_f32_e32 v5, v5
	v_mul_lo_u32 v0, v4, v5
	v_mul_hi_u32 v0, v5, v0
	v_add_u32_e32 v0, v5, v0
	v_mul_hi_u32 v0, v6, v0
	v_mul_lo_u32 v4, v0, v3
	v_sub_u32_e32 v4, v6, v4
	v_add_u32_e32 v5, 1, v0
	v_cmp_ge_u32_e32 vcc, v4, v3
	s_nop 1
	v_cndmask_b32_e32 v0, v0, v5, vcc
	v_sub_u32_e32 v5, v4, v3
	v_cndmask_b32_e32 v4, v4, v5, vcc
	v_add_u32_e32 v5, 1, v0
	v_cmp_ge_u32_e32 vcc, v4, v3
	v_add_u32_e32 v4, 1, v6
	s_nop 0
	v_cndmask_b32_e32 v0, v0, v5, vcc
	v_mul_lo_u32 v5, v3, v0
	v_add_u32_e32 v3, v5, v3
	v_cmp_ne_u32_e32 vcc, v4, v3
	s_and_saveexec_b64 s[0:1], vcc
	s_xor_b64 s[8:9], exec, s[0:1]
	s_cbranch_execz .LBB0_873
	s_waitcnt lgkmcnt(0)
	s_add_u32 s0, s96, 0x3500
	s_addc_u32 s1, s97, 0
	global_load_dword v2, v1, s[0:1] sc1
	s_waitcnt vmcnt(0)
	v_cmp_eq_u32_e32 vcc, v2, v0
	s_and_saveexec_b64 s[10:11], vcc
	s_cbranch_execz .LBB0_872
	s_mov_b32 s26, 1
	s_mov_b64 s[12:13], 0
	s_branch .LBB0_863
